# v26 + attention mid-loop slot rotation (3 SALU) moved in front of the first step's closing barrier
# speedup vs baseline: 1.0035x; 1.0035x over previous
; template<int THRL,int L,int NT> __device__ __forceinline__ void attn_unit(long rowbase,int kvh,int qblk,const bf16*Q,const bf16*__restrict__ K,const bf16*__restrict__ V,bf16*O,char*shm,const int tid){
;     ...
;   f32x16 pA0,pA1,pB0,pB1;
;   int sl_prev=0,sl_cur=0,sl_next=SLOTB;
.LBB0_879:
	s_waitcnt lgkmcnt(14)
	v_mfma_f32_32x32x16_bf16 v[2:17], v[158:161], v[178:181], v[2:17]
	v_exp_f32_e32 v98, v98
	v_exp_f32_e32 v99, v99
	v_exp_f32_e32 v100, v100
	v_exp_f32_e32 v101, v101
	s_waitcnt lgkmcnt(12)
	v_mfma_f32_32x32x16_bf16 v[18:33], v[158:161], v[174:177], v[18:33]
	v_exp_f32_e32 v102, v102
	v_exp_f32_e32 v103, v103
	v_exp_f32_e32 v104, v104
	v_exp_f32_e32 v105, v105
	v_add_u32_e32 v62, s18, v211
	ds_read_b128 v[58:61], v62
	ds_read_b128 v[114:117], v62 offset:512
	s_waitcnt lgkmcnt(12)
	v_mfma_f32_32x32x16_bf16 v[2:17], v[154:157], v[170:173], v[2:17]
	v_exp_f32_e32 v106, v106
	v_exp_f32_e32 v107, v107
	v_exp_f32_e32 v108, v108
	v_exp_f32_e32 v109, v109
	ds_read_b128 v[182:185], v62 offset:2048
	ds_read_b128 v[174:177], v62 offset:2560
	s_waitcnt lgkmcnt(12)
	v_mfma_f32_32x32x16_bf16 v[18:33], v[154:157], v[74:77], v[18:33]
	v_exp_f32_e32 v110, v110
	v_exp_f32_e32 v111, v111
	v_exp_f32_e32 v112, v112
	v_exp_f32_e32 v113, v113
	ds_read_b128 v[178:181], v62 offset:4096
	ds_read_b128 v[166:169], v62 offset:4608
	s_waitcnt lgkmcnt(12)
	v_mfma_f32_32x32x16_bf16 v[2:17], v[150:153], v[70:73], v[2:17]
	v_exp_f32_e32 v82, v82
	v_exp_f32_e32 v83, v83
	v_exp_f32_e32 v84, v84
	v_exp_f32_e32 v85, v85
	ds_read_b128 v[170:173], v62 offset:6144
	ds_read_b128 v[162:165], v62 offset:6656
	s_waitcnt lgkmcnt(12)
	v_mfma_f32_32x32x16_bf16 v[18:33], v[150:153], v[66:69], v[18:33]
	v_exp_f32_e32 v86, v86
	v_exp_f32_e32 v87, v87
	v_exp_f32_e32 v88, v88
	v_exp_f32_e32 v89, v89
	s_waitcnt lgkmcnt(10)
	v_mfma_f32_32x32x16_bf16 v[2:17], v[146:149], v[54:57], v[2:17]
	v_exp_f32_e32 v90, v90
	v_exp_f32_e32 v91, v91
	v_exp_f32_e32 v92, v92
	v_exp_f32_e32 v93, v93
	s_waitcnt lgkmcnt(8)
	v_mfma_f32_32x32x16_bf16 v[18:33], v[146:149], v[50:53], v[18:33]
	v_exp_f32_e32 v94, v94
	v_exp_f32_e32 v95, v95
	v_exp_f32_e32 v96, v96
	v_exp_f32_e32 v97, v97
	s_add_i32 s15, s18, 0x2000
	s_cmpk_lg_i32 s18, 0x4000
	s_cselect_b32 s65, s15, 0
	s_waitcnt vmcnt(2) lgkmcnt(0)
	s_barrier
	s_andn2_b64 vcc, exec, s[60:61]
	s_cbranch_vccnz .LBB0_881
	s_waitcnt lgkmcnt(0)
	v_add_u32_e32 v66, s92, v212
	ds_read_b128 v[50:53], v66 offset:49248
	ds_read_b128 v[54:57], v66 offset:49216
	ds_read_b128 v[62:65], v66 offset:49184
	ds_read_b128 v[66:69], v66 offset:49152
	s_waitcnt lgkmcnt(3)
	v_pk_mul_f32 v[14:15], v[14:15], v[50:51]
	s_waitcnt lgkmcnt(2)
	v_pk_mul_f32 v[10:11], v[10:11], v[54:55]
	s_waitcnt lgkmcnt(1)
	v_pk_mul_f32 v[6:7], v[6:7], v[62:63]
	v_pk_mul_f32 v[16:17], v[16:17], v[52:53]
	v_pk_mul_f32 v[12:13], v[12:13], v[56:57]
	v_pk_mul_f32 v[8:9], v[8:9], v[64:65]
	s_waitcnt lgkmcnt(0)
	v_pk_mul_f32 v[4:5], v[4:5], v[68:69]
	v_pk_mul_f32 v[2:3], v[2:3], v[66:67]
	v_pk_mul_f32 v[30:31], v[30:31], v[50:51]
	v_pk_mul_f32 v[26:27], v[26:27], v[54:55]
	v_pk_mul_f32 v[22:23], v[22:23], v[62:63]
	v_pk_mul_f32 v[32:33], v[32:33], v[52:53]
	v_pk_mul_f32 v[28:29], v[28:29], v[56:57]
	v_pk_mul_f32 v[24:25], v[24:25], v[64:65]
	v_pk_mul_f32 v[20:21], v[20:21], v[68:69]
	v_pk_mul_f32 v[18:19], v[18:19], v[66:67]
.LBB0_881:
	v_add_u32_e32 v214, s64, v209
	ds_read_b64_tr_b16 v[126:127], v214 offset:24576
	ds_read_b64_tr_b16 v[128:129], v214 offset:25088
	v_mfma_f32_32x32x16_bf16 v[66:81], v[58:61], v[142:145], v[34:49]
	v_add_f32_e32 v50, v98, v99
	v_add_f32_e32 v50, v100, v50
	v_add_f32_e32 v50, v101, v50
	v_add_f32_e32 v50, v102, v50
	v_add_f32_e32 v50, v103, v50
	v_cvt_pk_bf16_f32 v158, v98, v99
	v_cvt_pk_bf16_f32 v159, v100, v101
	ds_read_b64_tr_b16 v[122:123], v214 offset:28672
	ds_read_b64_tr_b16 v[124:125], v214 offset:29184
	v_add_f32_e32 v50, v104, v50
	v_add_f32_e32 v50, v105, v50
	v_add_f32_e32 v50, v106, v50
	v_add_f32_e32 v98, v107, v50
	v_mfma_f32_32x32x16_bf16 v[50:65], v[114:117], v[142:145], v[34:49]
	v_cvt_pk_bf16_f32 v160, v102, v103
	v_cvt_pk_bf16_f32 v161, v104, v105
	ds_read_b64_tr_b16 v[118:119], v214 offset:25600
	ds_read_b64_tr_b16 v[120:121], v214 offset:26112
	v_mfma_f32_32x32x16_bf16 v[66:81], v[182:185], v[138:141], v[66:81]
	v_add_f32_e32 v98, v108, v98
	v_add_f32_e32 v98, v109, v98
	v_add_f32_e32 v98, v110, v98
	v_add_f32_e32 v98, v111, v98
	v_cvt_pk_bf16_f32 v154, v106, v107
	v_cvt_pk_bf16_f32 v155, v108, v109
	ds_read_b64_tr_b16 v[114:115], v214 offset:29696
	ds_read_b64_tr_b16 v[116:117], v214 offset:30208
	v_mfma_f32_32x32x16_bf16 v[50:65], v[174:177], v[138:141], v[50:65]
	v_add_f32_e32 v98, v112, v98
	v_add_f32_e32 v98, v113, v98
	v_add_f32_e32 v98, v82, v98
	v_add_f32_e32 v98, v83, v98
	v_cvt_pk_bf16_f32 v156, v110, v111
	v_cvt_pk_bf16_f32 v157, v112, v113
	ds_read_b64_tr_b16 v[106:107], v214 offset:26624
	ds_read_b64_tr_b16 v[108:109], v214 offset:27136
	v_mfma_f32_32x32x16_bf16 v[66:81], v[178:181], v[134:137], v[66:81]
	v_add_f32_e32 v98, v84, v98
	v_add_f32_e32 v98, v85, v98
	v_add_f32_e32 v98, v86, v98
	v_add_f32_e32 v98, v87, v98
	v_cvt_pk_bf16_f32 v150, v82, v83
	v_cvt_pk_bf16_f32 v151, v84, v85
	ds_read_b64_tr_b16 v[102:103], v214 offset:30720
	ds_read_b64_tr_b16 v[104:105], v214 offset:31232
	v_mfma_f32_32x32x16_bf16 v[50:65], v[166:169], v[134:137], v[50:65]
	v_add_f32_e32 v82, v88, v98
	v_add_f32_e32 v82, v89, v82
	v_add_f32_e32 v82, v90, v82
	v_add_f32_e32 v82, v91, v82
	v_cvt_pk_bf16_f32 v152, v86, v87
	v_cvt_pk_bf16_f32 v153, v88, v89
	ds_read_b64_tr_b16 v[98:99], v214 offset:27648
	ds_read_b64_tr_b16 v[100:101], v214 offset:28160
	v_mfma_f32_32x32x16_bf16 v[66:81], v[170:173], v[130:133], v[66:81]
	v_add_f32_e32 v82, v92, v82
	v_add_f32_e32 v82, v93, v82
	v_add_f32_e32 v82, v94, v82
	v_add_f32_e32 v82, v95, v82
	v_cvt_pk_bf16_f32 v146, v90, v91
	v_cvt_pk_bf16_f32 v147, v92, v93
	ds_read_b64_tr_b16 v[86:87], v214 offset:31744
	ds_read_b64_tr_b16 v[88:89], v214 offset:32256
	v_mfma_f32_32x32x16_bf16 v[50:65], v[162:165], v[130:133], v[50:65]
	v_add_f32_e32 v82, v96, v82
	v_add_f32_e32 v82, v97, v82
	v_add_f32_e32 v84, 0, v82
	v_cvt_pk_bf16_f32 v148, v94, v95
	v_cvt_pk_bf16_f32 v149, v96, v97
	v_lshl_add_u64 v[82:83], v[196:197], 0, s[34:35]
	s_add_i32 s15, s18, s94
	s_mov_b32 m0, s15
	s_nop 0
	global_load_lds_dwordx4 v[82:83], off
	v_max_f32_e32 v82, v66, v67
	s_nop 1
	v_max3_f32 v83, v68, v69, v51
	v_max3_f32 v82, v82, v50, v52
	v_max3_f32 v82, v82, v53, v70
	v_max3_f32 v83, v83, v72, v73
	v_max3_f32 v82, v82, v71, v54
	v_max3_f32 v83, v83, v56, v57
	v_max3_f32 v82, v82, v55, v74
	v_max3_f32 v83, v83, v76, v77
	v_max3_f32 v82, v82, v75, v58
	v_max3_f32 v83, v83, v60, v61
	v_max3_f32 v82, v82, v59, v78
	v_max3_f32 v83, v83, v80, v81
	v_max3_f32 v82, v82, v79, v62
	v_max3_f32 v83, v83, v64, v65
	v_max3_f32 v82, v82, v63, v83
	v_mov_b32_e32 v83, v82
	s_nop 1
	v_permlane32_swap_b32_e32 v82, v83
	v_max_f32_e32 v82, v82, v83
	v_lshl_add_u64 v[188:189], v[188:189], 0, s[28:29]
	s_add_i32 s15, s65, s93
	s_mov_b32 m0, s15
	s_nop 0
	global_load_lds_dwordx4 v[188:189], off
	v_cmp_lt_f32_e32 vcc, s83, v82
	s_cmp_lg_u64 vcc, 0
	v_add_f32_e32 v182, v213, v84
	s_cselect_b64 s[60:61], -1, 0
	s_cbranch_vccnz .LBB0_889

; #define WAIT_BAR(N) asm volatile("s_waitcnt vmcnt(" #N ") lgkmcnt(0)\n\ts_barrier":::"memory")
;   #define RESC() do{ if(resc){ asm volatile("s_waitcnt lgkmcnt(0)":::"memory"); \
;       _Pragma("unroll") for(int d_=0;d_<2;++d_) _Pragma("unroll") for(int r=0;r<16;++r)o[d_][r]*=wsf[crow(r,hi)]; } }while(0)
;   #define ROT() do{sl_prev=sl_cur;sl_cur=sl_next;sl_next=(sl_next==(NSLOT-1)*SLOTB)?0:sl_next+SLOTB;}while(0)
; template<int THRL,int L,int NT> __device__ __forceinline__ void attn_unit(long rowbase,int kvh,int qblk,const bf16*Q,const bf16*__restrict__ K,const bf16*__restrict__ V,bf16*O,char*shm,const int tid){
;     ...
;   int t=1;
;     ...
;   for(;t+5<NT;t+=2){
;     STEP(pB0,pB1,pA0,pA1,t,true,true,true);     WAIT_BAR(2); RESC(); ROT();
;     STEP(pA0,pA1,pB0,pB1,t+1,true,true,true);   WAIT_BAR(2); RESC(); ROT();
.LBB0_920:
	s_waitcnt lgkmcnt(14)
	v_mfma_f32_32x32x16_bf16 v[2:17], v[158:161], v[178:181], v[2:17]
	v_exp_f32_e32 v98, v98
	v_exp_f32_e32 v99, v99
	v_exp_f32_e32 v100, v100
	v_exp_f32_e32 v101, v101
	s_waitcnt lgkmcnt(12)
	v_mfma_f32_32x32x16_bf16 v[18:33], v[158:161], v[174:177], v[18:33]
	v_exp_f32_e32 v102, v102
	v_exp_f32_e32 v103, v103
	v_exp_f32_e32 v104, v104
	v_exp_f32_e32 v105, v105
	v_add_u32_e32 v62, s95, v210
	ds_read_b128 v[58:61], v62
	ds_read_b128 v[114:117], v62 offset:512
	s_waitcnt lgkmcnt(12)
	v_mfma_f32_32x32x16_bf16 v[2:17], v[154:157], v[170:173], v[2:17]
	v_exp_f32_e32 v106, v106
	v_exp_f32_e32 v107, v107
	v_exp_f32_e32 v108, v108
	v_exp_f32_e32 v109, v109
	ds_read_b128 v[182:185], v62 offset:2048
	ds_read_b128 v[174:177], v62 offset:2560
	s_waitcnt lgkmcnt(12)
	v_mfma_f32_32x32x16_bf16 v[18:33], v[154:157], v[74:77], v[18:33]
	v_exp_f32_e32 v110, v110
	v_exp_f32_e32 v111, v111
	v_exp_f32_e32 v112, v112
	v_exp_f32_e32 v113, v113
	ds_read_b128 v[178:181], v62 offset:4096
	ds_read_b128 v[166:169], v62 offset:4608
	s_waitcnt lgkmcnt(12)
	v_mfma_f32_32x32x16_bf16 v[2:17], v[150:153], v[70:73], v[2:17]
	v_exp_f32_e32 v82, v82
	v_exp_f32_e32 v83, v83
	v_exp_f32_e32 v84, v84
	v_exp_f32_e32 v85, v85
	ds_read_b128 v[170:173], v62 offset:6144
	ds_read_b128 v[162:165], v62 offset:6656
	s_waitcnt lgkmcnt(12)
	v_mfma_f32_32x32x16_bf16 v[18:33], v[150:153], v[66:69], v[18:33]
	v_exp_f32_e32 v86, v86
	v_exp_f32_e32 v87, v87
	v_exp_f32_e32 v88, v88
	v_exp_f32_e32 v89, v89
	s_waitcnt lgkmcnt(10)
	v_mfma_f32_32x32x16_bf16 v[2:17], v[146:149], v[54:57], v[2:17]
	v_exp_f32_e32 v90, v90
	v_exp_f32_e32 v91, v91
	v_exp_f32_e32 v92, v92
	v_exp_f32_e32 v93, v93
	s_waitcnt lgkmcnt(8)
	v_mfma_f32_32x32x16_bf16 v[18:33], v[146:149], v[50:53], v[18:33]
	v_exp_f32_e32 v94, v94
	v_exp_f32_e32 v95, v95
	v_exp_f32_e32 v96, v96
	v_exp_f32_e32 v97, v97
	s_add_i32 s15, s95, 0x2000
	s_cmpk_lg_i32 s95, 0x4000
	s_cselect_b32 s65, s15, 0
	s_waitcnt vmcnt(2) lgkmcnt(0)
	s_barrier
	s_andn2_b64 vcc, exec, s[60:61]
	s_cbranch_vccnz .LBB0_922
	s_waitcnt lgkmcnt(0)
	v_add_u32_e32 v66, s92, v211
	ds_read_b128 v[50:53], v66 offset:49248
	ds_read_b128 v[54:57], v66 offset:49216
	ds_read_b128 v[62:65], v66 offset:49184
	ds_read_b128 v[66:69], v66 offset:49152
	s_waitcnt lgkmcnt(3)
	v_pk_mul_f32 v[14:15], v[14:15], v[50:51]
	s_waitcnt lgkmcnt(2)
	v_pk_mul_f32 v[10:11], v[10:11], v[54:55]
	s_waitcnt lgkmcnt(1)
	v_pk_mul_f32 v[6:7], v[6:7], v[62:63]
	v_pk_mul_f32 v[16:17], v[16:17], v[52:53]
	v_pk_mul_f32 v[12:13], v[12:13], v[56:57]
	v_pk_mul_f32 v[8:9], v[8:9], v[64:65]
	s_waitcnt lgkmcnt(0)
	v_pk_mul_f32 v[4:5], v[4:5], v[68:69]
	v_pk_mul_f32 v[2:3], v[2:3], v[66:67]
	v_pk_mul_f32 v[30:31], v[30:31], v[50:51]
	v_pk_mul_f32 v[26:27], v[26:27], v[54:55]
	v_pk_mul_f32 v[22:23], v[22:23], v[62:63]
	v_pk_mul_f32 v[32:33], v[32:33], v[52:53]
	v_pk_mul_f32 v[28:29], v[28:29], v[56:57]
	v_pk_mul_f32 v[24:25], v[24:25], v[64:65]
	v_pk_mul_f32 v[20:21], v[20:21], v[68:69]
	v_pk_mul_f32 v[18:19], v[18:19], v[66:67]
.LBB0_922:
	v_add_u32_e32 v203, s64, v208
	ds_read_b64_tr_b16 v[126:127], v203 offset:24576
	ds_read_b64_tr_b16 v[128:129], v203 offset:25088
	v_mfma_f32_32x32x16_bf16 v[66:81], v[58:61], v[142:145], v[34:49]
	v_add_f32_e32 v50, v98, v99
	v_add_f32_e32 v50, v100, v50
	v_add_f32_e32 v50, v101, v50
	v_add_f32_e32 v50, v102, v50
	v_add_f32_e32 v50, v103, v50
	v_cvt_pk_bf16_f32 v158, v98, v99
	v_cvt_pk_bf16_f32 v159, v100, v101
	ds_read_b64_tr_b16 v[122:123], v203 offset:28672
	ds_read_b64_tr_b16 v[124:125], v203 offset:29184
	v_add_f32_e32 v50, v104, v50
	v_add_f32_e32 v50, v105, v50
	v_add_f32_e32 v50, v106, v50
	v_add_f32_e32 v98, v107, v50
	v_mfma_f32_32x32x16_bf16 v[50:65], v[114:117], v[142:145], v[34:49]
	v_cvt_pk_bf16_f32 v160, v102, v103
	v_cvt_pk_bf16_f32 v161, v104, v105
	ds_read_b64_tr_b16 v[118:119], v203 offset:25600
	ds_read_b64_tr_b16 v[120:121], v203 offset:26112
	v_mfma_f32_32x32x16_bf16 v[66:81], v[182:185], v[138:141], v[66:81]
	v_add_f32_e32 v98, v108, v98
	v_add_f32_e32 v98, v109, v98
	v_add_f32_e32 v98, v110, v98
	v_add_f32_e32 v98, v111, v98
	v_cvt_pk_bf16_f32 v154, v106, v107
	v_cvt_pk_bf16_f32 v155, v108, v109
	ds_read_b64_tr_b16 v[114:115], v203 offset:29696
	ds_read_b64_tr_b16 v[116:117], v203 offset:30208
	v_mfma_f32_32x32x16_bf16 v[50:65], v[174:177], v[138:141], v[50:65]
	v_add_f32_e32 v98, v112, v98
	v_add_f32_e32 v98, v113, v98
	v_add_f32_e32 v98, v82, v98
	v_add_f32_e32 v98, v83, v98
	v_cvt_pk_bf16_f32 v156, v110, v111
	v_cvt_pk_bf16_f32 v157, v112, v113
	ds_read_b64_tr_b16 v[106:107], v203 offset:26624
	ds_read_b64_tr_b16 v[108:109], v203 offset:27136
	v_mfma_f32_32x32x16_bf16 v[66:81], v[178:181], v[134:137], v[66:81]
	v_add_f32_e32 v98, v84, v98
	v_add_f32_e32 v98, v85, v98
	v_add_f32_e32 v98, v86, v98
	v_add_f32_e32 v98, v87, v98
	v_cvt_pk_bf16_f32 v150, v82, v83
	v_cvt_pk_bf16_f32 v151, v84, v85
	ds_read_b64_tr_b16 v[102:103], v203 offset:30720
	ds_read_b64_tr_b16 v[104:105], v203 offset:31232
	v_mfma_f32_32x32x16_bf16 v[50:65], v[166:169], v[134:137], v[50:65]
	v_add_f32_e32 v82, v88, v98
	v_add_f32_e32 v82, v89, v82
	v_add_f32_e32 v82, v90, v82
	v_add_f32_e32 v82, v91, v82
	v_cvt_pk_bf16_f32 v152, v86, v87
	v_cvt_pk_bf16_f32 v153, v88, v89
	ds_read_b64_tr_b16 v[98:99], v203 offset:27648
	ds_read_b64_tr_b16 v[100:101], v203 offset:28160
	v_mfma_f32_32x32x16_bf16 v[66:81], v[170:173], v[130:133], v[66:81]
	v_add_f32_e32 v82, v92, v82
	v_add_f32_e32 v82, v93, v82
	v_add_f32_e32 v82, v94, v82
	v_add_f32_e32 v82, v95, v82
	v_cvt_pk_bf16_f32 v146, v90, v91
	v_cvt_pk_bf16_f32 v147, v92, v93
	ds_read_b64_tr_b16 v[86:87], v203 offset:31744
	ds_read_b64_tr_b16 v[88:89], v203 offset:32256
	v_mfma_f32_32x32x16_bf16 v[50:65], v[162:165], v[130:133], v[50:65]
	v_add_f32_e32 v82, v96, v82
	v_add_f32_e32 v82, v97, v82
	v_add_f32_e32 v84, 0, v82
	v_cvt_pk_bf16_f32 v148, v94, v95
	v_cvt_pk_bf16_f32 v149, v96, v97
	v_lshl_add_u64 v[82:83], v[196:197], 0, s[34:35]
	s_add_i32 s15, s95, s93
	s_mov_b32 m0, s15
	s_nop 0
	global_load_lds_dwordx4 v[82:83], off
	v_max_f32_e32 v82, v66, v67
	s_nop 1
	v_max3_f32 v83, v68, v69, v51
	v_max3_f32 v82, v82, v50, v52
	v_max3_f32 v82, v82, v53, v70
	v_max3_f32 v83, v83, v72, v73
	v_max3_f32 v82, v82, v71, v54
	v_max3_f32 v83, v83, v56, v57
	v_max3_f32 v82, v82, v55, v74
	v_max3_f32 v83, v83, v76, v77
	v_max3_f32 v82, v82, v75, v58
	v_max3_f32 v83, v83, v60, v61
	v_max3_f32 v82, v82, v59, v78
	v_max3_f32 v83, v83, v80, v81
	v_max3_f32 v82, v82, v79, v62
	v_max3_f32 v83, v83, v64, v65
	v_max3_f32 v82, v82, v63, v83
	v_mov_b32_e32 v83, v82
	s_nop 1
	v_permlane32_swap_b32_e32 v82, v83
	v_max_f32_e32 v82, v82, v83
	v_lshl_add_u64 v[188:189], v[188:189], 0, s[28:29]
	s_add_i32 s15, s65, s69
	s_mov_b32 m0, s15
	s_nop 0
	global_load_lds_dwordx4 v[188:189], off
	v_cmp_lt_f32_e32 vcc, s83, v82
	s_cmp_lg_u64 vcc, 0
	v_add_f32_e32 v182, v192, v84
	s_cselect_b64 s[60:61], -1, 0
	s_cbranch_vccnz .LBB0_930

; #define WAIT_BAR(N) asm volatile("s_waitcnt vmcnt(" #N ") lgkmcnt(0)\n\ts_barrier":::"memory")
;   #define RESC() do{ if(resc){ asm volatile("s_waitcnt lgkmcnt(0)":::"memory"); \
;       _Pragma("unroll") for(int d_=0;d_<2;++d_) _Pragma("unroll") for(int r=0;r<16;++r)o[d_][r]*=wsf[crow(r,hi)]; } }while(0)
;   #define ROT() do{sl_prev=sl_cur;sl_cur=sl_next;sl_next=(sl_next==(NSLOT-1)*SLOTB)?0:sl_next+SLOTB;}while(0)
; template<int THRL,int L,int NT> __device__ __forceinline__ void attn_unit(long rowbase,int kvh,int qblk,const bf16*Q,const bf16*__restrict__ K,const bf16*__restrict__ V,bf16*O,char*shm,const int tid){
;     ...
;   int t=1;
;     ...
;   for(;t+5<NT;t+=2){
;     STEP(pB0,pB1,pA0,pA1,t,true,true,true);     WAIT_BAR(2); RESC(); ROT();
;     STEP(pA0,pA1,pB0,pB1,t+1,true,true,true);   WAIT_BAR(2); RESC(); ROT();
.LBB0_2478:
	s_waitcnt lgkmcnt(14)
	v_mfma_f32_32x32x16_bf16 v[2:17], v[158:161], v[178:181], v[2:17]
	v_exp_f32_e32 v98, v98
	v_exp_f32_e32 v99, v99
	v_exp_f32_e32 v100, v100
	v_exp_f32_e32 v101, v101
	s_waitcnt lgkmcnt(12)
	v_mfma_f32_32x32x16_bf16 v[18:33], v[158:161], v[174:177], v[18:33]
	v_exp_f32_e32 v102, v102
	v_exp_f32_e32 v103, v103
	v_exp_f32_e32 v104, v104
	v_exp_f32_e32 v105, v105
	v_add_u32_e32 v62, s96, v211
	ds_read_b128 v[58:61], v62
	ds_read_b128 v[114:117], v62 offset:512
	s_waitcnt lgkmcnt(12)
	v_mfma_f32_32x32x16_bf16 v[2:17], v[154:157], v[170:173], v[2:17]
	v_exp_f32_e32 v106, v106
	v_exp_f32_e32 v107, v107
	v_exp_f32_e32 v108, v108
	v_exp_f32_e32 v109, v109
	ds_read_b128 v[182:185], v62 offset:2048
	ds_read_b128 v[174:177], v62 offset:2560
	s_waitcnt lgkmcnt(12)
	v_mfma_f32_32x32x16_bf16 v[18:33], v[154:157], v[74:77], v[18:33]
	v_exp_f32_e32 v110, v110
	v_exp_f32_e32 v111, v111
	v_exp_f32_e32 v112, v112
	v_exp_f32_e32 v113, v113
	ds_read_b128 v[178:181], v62 offset:4096
	ds_read_b128 v[166:169], v62 offset:4608
	s_waitcnt lgkmcnt(12)
	v_mfma_f32_32x32x16_bf16 v[2:17], v[150:153], v[70:73], v[2:17]
	v_exp_f32_e32 v82, v82
	v_exp_f32_e32 v83, v83
	v_exp_f32_e32 v84, v84
	v_exp_f32_e32 v85, v85
	ds_read_b128 v[170:173], v62 offset:6144
	ds_read_b128 v[162:165], v62 offset:6656
	s_waitcnt lgkmcnt(12)
	v_mfma_f32_32x32x16_bf16 v[18:33], v[150:153], v[66:69], v[18:33]
	v_exp_f32_e32 v86, v86
	v_exp_f32_e32 v87, v87
	v_exp_f32_e32 v88, v88
	v_exp_f32_e32 v89, v89
	s_waitcnt lgkmcnt(10)
	v_mfma_f32_32x32x16_bf16 v[2:17], v[146:149], v[54:57], v[2:17]
	v_exp_f32_e32 v90, v90
	v_exp_f32_e32 v91, v91
	v_exp_f32_e32 v92, v92
	v_exp_f32_e32 v93, v93
	s_waitcnt lgkmcnt(8)
	v_mfma_f32_32x32x16_bf16 v[18:33], v[146:149], v[50:53], v[18:33]
	v_exp_f32_e32 v94, v94
	v_exp_f32_e32 v95, v95
	v_exp_f32_e32 v96, v96
	v_exp_f32_e32 v97, v97
	s_add_i32 s15, s96, 0x2000
	s_cmpk_lg_i32 s96, 0x4000
	s_cselect_b32 s65, s15, 0
	s_waitcnt vmcnt(2) lgkmcnt(0)
	s_barrier
	s_andn2_b64 vcc, exec, s[60:61]
	s_cbranch_vccnz .LBB0_2480
	s_waitcnt lgkmcnt(0)
	v_add_u32_e32 v66, s92, v212
	ds_read_b128 v[50:53], v66 offset:49248
	ds_read_b128 v[54:57], v66 offset:49216
	ds_read_b128 v[62:65], v66 offset:49184
	ds_read_b128 v[66:69], v66 offset:49152
	s_waitcnt lgkmcnt(3)
	v_pk_mul_f32 v[14:15], v[14:15], v[50:51]
	s_waitcnt lgkmcnt(2)
	v_pk_mul_f32 v[10:11], v[10:11], v[54:55]
	s_waitcnt lgkmcnt(1)
	v_pk_mul_f32 v[6:7], v[6:7], v[62:63]
	v_pk_mul_f32 v[16:17], v[16:17], v[52:53]
	v_pk_mul_f32 v[12:13], v[12:13], v[56:57]
	v_pk_mul_f32 v[8:9], v[8:9], v[64:65]
	s_waitcnt lgkmcnt(0)
	v_pk_mul_f32 v[4:5], v[4:5], v[68:69]
	v_pk_mul_f32 v[2:3], v[2:3], v[66:67]
	v_pk_mul_f32 v[30:31], v[30:31], v[50:51]
	v_pk_mul_f32 v[26:27], v[26:27], v[54:55]
	v_pk_mul_f32 v[22:23], v[22:23], v[62:63]
	v_pk_mul_f32 v[32:33], v[32:33], v[52:53]
	v_pk_mul_f32 v[28:29], v[28:29], v[56:57]
	v_pk_mul_f32 v[24:25], v[24:25], v[64:65]
	v_pk_mul_f32 v[20:21], v[20:21], v[68:69]
	v_pk_mul_f32 v[18:19], v[18:19], v[66:67]
.LBB0_2480:
	v_add_u32_e32 v214, s64, v209
	ds_read_b64_tr_b16 v[126:127], v214 offset:24576
	ds_read_b64_tr_b16 v[128:129], v214 offset:25088
	v_mfma_f32_32x32x16_bf16 v[66:81], v[58:61], v[142:145], v[34:49]
	v_add_f32_e32 v50, v98, v99
	v_add_f32_e32 v50, v100, v50
	v_add_f32_e32 v50, v101, v50
	v_add_f32_e32 v50, v102, v50
	v_add_f32_e32 v50, v103, v50
	v_cvt_pk_bf16_f32 v158, v98, v99
	v_cvt_pk_bf16_f32 v159, v100, v101
	ds_read_b64_tr_b16 v[122:123], v214 offset:28672
	ds_read_b64_tr_b16 v[124:125], v214 offset:29184
	v_add_f32_e32 v50, v104, v50
	v_add_f32_e32 v50, v105, v50
	v_add_f32_e32 v50, v106, v50
	v_add_f32_e32 v98, v107, v50
	v_mfma_f32_32x32x16_bf16 v[50:65], v[114:117], v[142:145], v[34:49]
	v_cvt_pk_bf16_f32 v160, v102, v103
	v_cvt_pk_bf16_f32 v161, v104, v105
	ds_read_b64_tr_b16 v[118:119], v214 offset:25600
	ds_read_b64_tr_b16 v[120:121], v214 offset:26112
	v_mfma_f32_32x32x16_bf16 v[66:81], v[182:185], v[138:141], v[66:81]
	v_add_f32_e32 v98, v108, v98
	v_add_f32_e32 v98, v109, v98
	v_add_f32_e32 v98, v110, v98
	v_add_f32_e32 v98, v111, v98
	v_cvt_pk_bf16_f32 v154, v106, v107
	v_cvt_pk_bf16_f32 v155, v108, v109
	ds_read_b64_tr_b16 v[114:115], v214 offset:29696
	ds_read_b64_tr_b16 v[116:117], v214 offset:30208
	v_mfma_f32_32x32x16_bf16 v[50:65], v[174:177], v[138:141], v[50:65]
	v_add_f32_e32 v98, v112, v98
	v_add_f32_e32 v98, v113, v98
	v_add_f32_e32 v98, v82, v98
	v_add_f32_e32 v98, v83, v98
	v_cvt_pk_bf16_f32 v156, v110, v111
	v_cvt_pk_bf16_f32 v157, v112, v113
	ds_read_b64_tr_b16 v[106:107], v214 offset:26624
	ds_read_b64_tr_b16 v[108:109], v214 offset:27136
	v_mfma_f32_32x32x16_bf16 v[66:81], v[178:181], v[134:137], v[66:81]
	v_add_f32_e32 v98, v84, v98
	v_add_f32_e32 v98, v85, v98
	v_add_f32_e32 v98, v86, v98
	v_add_f32_e32 v98, v87, v98
	v_cvt_pk_bf16_f32 v150, v82, v83
	v_cvt_pk_bf16_f32 v151, v84, v85
	ds_read_b64_tr_b16 v[102:103], v214 offset:30720
	ds_read_b64_tr_b16 v[104:105], v214 offset:31232
	v_mfma_f32_32x32x16_bf16 v[50:65], v[166:169], v[134:137], v[50:65]
	v_add_f32_e32 v82, v88, v98
	v_add_f32_e32 v82, v89, v82
	v_add_f32_e32 v82, v90, v82
	v_add_f32_e32 v82, v91, v82
	v_cvt_pk_bf16_f32 v152, v86, v87
	v_cvt_pk_bf16_f32 v153, v88, v89
	ds_read_b64_tr_b16 v[98:99], v214 offset:27648
	ds_read_b64_tr_b16 v[100:101], v214 offset:28160
	v_mfma_f32_32x32x16_bf16 v[66:81], v[170:173], v[130:133], v[66:81]
	v_add_f32_e32 v82, v92, v82
	v_add_f32_e32 v82, v93, v82
	v_add_f32_e32 v82, v94, v82
	v_add_f32_e32 v82, v95, v82
	v_cvt_pk_bf16_f32 v146, v90, v91
	v_cvt_pk_bf16_f32 v147, v92, v93
	ds_read_b64_tr_b16 v[86:87], v214 offset:31744
	ds_read_b64_tr_b16 v[88:89], v214 offset:32256
	v_mfma_f32_32x32x16_bf16 v[50:65], v[162:165], v[130:133], v[50:65]
	v_add_f32_e32 v82, v96, v82
	v_add_f32_e32 v82, v97, v82
	v_add_f32_e32 v84, 0, v82
	v_cvt_pk_bf16_f32 v148, v94, v95
	v_cvt_pk_bf16_f32 v149, v96, v97
	v_lshl_add_u64 v[82:83], v[196:197], 0, s[34:35]
	s_add_i32 s15, s96, s94
	s_mov_b32 m0, s15
	s_nop 0
	global_load_lds_dwordx4 v[82:83], off
	v_max_f32_e32 v82, v66, v67
	s_nop 1
	v_max3_f32 v83, v68, v69, v51
	v_max3_f32 v82, v82, v50, v52
	v_max3_f32 v82, v82, v53, v70
	v_max3_f32 v83, v83, v72, v73
	v_max3_f32 v82, v82, v71, v54
	v_max3_f32 v83, v83, v56, v57
	v_max3_f32 v82, v82, v55, v74
	v_max3_f32 v83, v83, v76, v77
	v_max3_f32 v82, v82, v75, v58
	v_max3_f32 v83, v83, v60, v61
	v_max3_f32 v82, v82, v59, v78
	v_max3_f32 v83, v83, v80, v81
	v_max3_f32 v82, v82, v79, v62
	v_max3_f32 v83, v83, v64, v65
	v_max3_f32 v82, v82, v63, v83
	v_mov_b32_e32 v83, v82
	s_nop 1
	v_permlane32_swap_b32_e32 v82, v83
	v_max_f32_e32 v82, v82, v83
	v_lshl_add_u64 v[188:189], v[188:189], 0, s[28:29]
	s_add_i32 s15, s65, s93
	s_mov_b32 m0, s15
	s_nop 0
	global_load_lds_dwordx4 v[188:189], off
	v_cmp_lt_f32_e32 vcc, s82, v82
	s_cmp_lg_u64 vcc, 0
	v_add_f32_e32 v182, v213, v84
	s_cselect_b64 s[60:61], -1, 0
	s_cbranch_vccnz .LBB0_2488

.LBB0_2521:
	v_add_u32_e32 v203, s64, v208
	ds_read_b64_tr_b16 v[126:127], v203 offset:24576
	ds_read_b64_tr_b16 v[128:129], v203 offset:25088
	v_mfma_f32_32x32x16_bf16 v[66:81], v[58:61], v[142:145], v[34:49]
	v_add_f32_e32 v50, v98, v99
	v_add_f32_e32 v50, v100, v50
	v_add_f32_e32 v50, v101, v50
	v_add_f32_e32 v50, v102, v50
	v_add_f32_e32 v50, v103, v50
	v_cvt_pk_bf16_f32 v158, v98, v99
	v_cvt_pk_bf16_f32 v159, v100, v101
	ds_read_b64_tr_b16 v[122:123], v203 offset:28672
	ds_read_b64_tr_b16 v[124:125], v203 offset:29184
	v_add_f32_e32 v50, v104, v50
	v_add_f32_e32 v50, v105, v50
	v_add_f32_e32 v50, v106, v50
	v_add_f32_e32 v98, v107, v50
	v_mfma_f32_32x32x16_bf16 v[50:65], v[114:117], v[142:145], v[34:49]
	v_cvt_pk_bf16_f32 v160, v102, v103
	v_cvt_pk_bf16_f32 v161, v104, v105
	ds_read_b64_tr_b16 v[118:119], v203 offset:25600
	ds_read_b64_tr_b16 v[120:121], v203 offset:26112
	v_mfma_f32_32x32x16_bf16 v[66:81], v[182:185], v[138:141], v[66:81]
	v_add_f32_e32 v98, v108, v98
	v_add_f32_e32 v98, v109, v98
	v_add_f32_e32 v98, v110, v98
	v_add_f32_e32 v98, v111, v98
	v_cvt_pk_bf16_f32 v154, v106, v107
	v_cvt_pk_bf16_f32 v155, v108, v109
	ds_read_b64_tr_b16 v[114:115], v203 offset:29696
	ds_read_b64_tr_b16 v[116:117], v203 offset:30208
	v_mfma_f32_32x32x16_bf16 v[50:65], v[174:177], v[138:141], v[50:65]
	v_add_f32_e32 v98, v112, v98
	v_add_f32_e32 v98, v113, v98
	v_add_f32_e32 v98, v82, v98
	v_add_f32_e32 v98, v83, v98
	v_cvt_pk_bf16_f32 v156, v110, v111
	v_cvt_pk_bf16_f32 v157, v112, v113
	ds_read_b64_tr_b16 v[106:107], v203 offset:26624
	ds_read_b64_tr_b16 v[108:109], v203 offset:27136
	v_mfma_f32_32x32x16_bf16 v[66:81], v[178:181], v[134:137], v[66:81]
	v_add_f32_e32 v98, v84, v98
	v_add_f32_e32 v98, v85, v98
	v_add_f32_e32 v98, v86, v98
	v_add_f32_e32 v98, v87, v98
	v_cvt_pk_bf16_f32 v150, v82, v83
	v_cvt_pk_bf16_f32 v151, v84, v85
	ds_read_b64_tr_b16 v[102:103], v203 offset:30720
	ds_read_b64_tr_b16 v[104:105], v203 offset:31232
	v_mfma_f32_32x32x16_bf16 v[50:65], v[166:169], v[134:137], v[50:65]
	v_add_f32_e32 v82, v88, v98
	v_add_f32_e32 v82, v89, v82
	v_add_f32_e32 v82, v90, v82
	v_add_f32_e32 v82, v91, v82
	v_cvt_pk_bf16_f32 v152, v86, v87
	v_cvt_pk_bf16_f32 v153, v88, v89
	ds_read_b64_tr_b16 v[98:99], v203 offset:27648
	ds_read_b64_tr_b16 v[100:101], v203 offset:28160
	v_mfma_f32_32x32x16_bf16 v[66:81], v[170:173], v[130:133], v[66:81]
	v_add_f32_e32 v82, v92, v82
	v_add_f32_e32 v82, v93, v82
	v_add_f32_e32 v82, v94, v82
	v_add_f32_e32 v82, v95, v82
	v_cvt_pk_bf16_f32 v146, v90, v91
	v_cvt_pk_bf16_f32 v147, v92, v93
	ds_read_b64_tr_b16 v[86:87], v203 offset:31744
	ds_read_b64_tr_b16 v[88:89], v203 offset:32256
	v_mfma_f32_32x32x16_bf16 v[50:65], v[162:165], v[130:133], v[50:65]
	v_add_f32_e32 v82, v96, v82
	v_add_f32_e32 v82, v97, v82
	v_add_f32_e32 v84, 0, v82
	v_cvt_pk_bf16_f32 v148, v94, v95
	v_cvt_pk_bf16_f32 v149, v96, v97
	v_lshl_add_u64 v[82:83], v[196:197], 0, s[34:35]
	s_add_i32 s15, s95, s93
	s_mov_b32 m0, s15
	s_nop 0
	global_load_lds_dwordx4 v[82:83], off
	v_max_f32_e32 v82, v66, v67
	s_nop 1
	v_max3_f32 v83, v68, v69, v51
	v_max3_f32 v82, v82, v50, v52
	v_max3_f32 v82, v82, v53, v70
	v_max3_f32 v83, v83, v72, v73
	v_max3_f32 v82, v82, v71, v54
	v_max3_f32 v83, v83, v56, v57
	v_max3_f32 v82, v82, v55, v74
	v_max3_f32 v83, v83, v76, v77
	v_max3_f32 v82, v82, v75, v58
	v_max3_f32 v83, v83, v60, v61
	v_max3_f32 v82, v82, v59, v78
	v_max3_f32 v83, v83, v80, v81
	v_max3_f32 v82, v82, v79, v62
	v_max3_f32 v83, v83, v64, v65
	v_max3_f32 v82, v82, v63, v83
	v_mov_b32_e32 v83, v82
	s_nop 1
	v_permlane32_swap_b32_e32 v82, v83
	v_max_f32_e32 v82, v82, v83
	v_lshl_add_u64 v[188:189], v[188:189], 0, s[28:29]
	s_add_i32 s15, s65, s69
	s_mov_b32 m0, s15
	s_nop 0
	global_load_lds_dwordx4 v[188:189], off
	v_cmp_lt_f32_e32 vcc, s82, v82
	s_cmp_lg_u64 vcc, 0
	v_add_f32_e32 v182, v192, v84
	s_cselect_b64 s[60:61], -1, 0
	s_cbranch_vccnz .LBB0_2529
